# attention A blocks in reverse order (1535-L): most recently written q/k/v columns read first (memory-side cache reuse)
# speedup vs baseline: 1.0049x; 1.0027x over previous
.LBB0_966:
	s_and_b64 vcc, exec, s[4:5]
	s_cbranch_vccz .LBB0_1175
	v_readlane_b32 s4, v255, 0
	v_readlane_b32 s5, v255, 1
	v_readlane_b32 s13, v255, 2
	s_mov_b32 s72, s97
	v_mbcnt_lo_u32_b32 v14, -1, 0
	v_mbcnt_hi_u32_b32 v14, -1, v14
	s_cmpk_gt_i32 s72, 0x5ff
	s_cbranch_scc1 .LBB0_1175
	s_load_dwordx2 s[0:1], s[4:5], 0xc0
	v_readlane_b32 s2, v255, 11
	v_lshlrev_b32_e32 v17, 3, v14
	v_and_b32_e32 v0, 0x78, v17
	v_add_u32_e32 v15, s2, v14
	s_waitcnt lgkmcnt(0)
	s_add_u32 s73, s0, 0x2a800000
	s_addc_u32 s74, s1, 0
	s_add_u32 s75, s0, 0x3c800000
	s_addc_u32 s76, s1, 0
	s_add_u32 s77, s0, 0x400000
	s_addc_u32 s78, s1, 0
	s_sub_i32 s90, 0x5ff, s72
	s_ashr_i32 s0, s90, 9
	s_lshl_b32 s6, s0, 1
	s_lshr_b32 s3, 16, s6
	s_and_b32 s1, s90, 15
	s_sub_i32 s2, 4, s6
	s_add_i32 s3, s3, -1
	s_lshr_b32 s2, s1, s2
	s_and_b32 s14, s3, s1
	s_lshl_b32 s1, s90, 5
	s_and_b32 s1, s1, 0x3000
	s_or_b32 s1, s2, s1
	s_add_i32 s2, s6, 8
	s_bfe_u32 s7, s90, 0x30004
	s_lshl_b64 s[2:3], s[14:15], s2
	s_add_u32 s2, s2, s1
	s_addc_u32 s3, s3, 0
	s_mul_i32 s4, s3, 0x4800
	s_mul_hi_u32 s5, s2, 0x4800
	s_add_i32 s5, s5, s4
	s_mul_i32 s4, s2, 0x4800
	s_add_u32 s8, s73, s4
	s_mul_i32 s4, s0, 0xc00
	s_addc_u32 s9, s74, s5
	s_ashr_i32 s5, s4, 31
	s_lshl_b64 s[4:5], s[4:5], 1
	s_add_u32 s8, s8, s4
	s_addc_u32 s9, s9, s5
	s_lshl_b32 s10, s7, 8
	s_add_u32 s8, s8, s10
	s_addc_u32 s9, s9, 0
	s_mulk_i32 s1, 0x4800
	s_add_u32 s1, s73, s1
	s_addc_u32 s11, s74, 0
	s_add_u32 s1, s1, s4
	s_addc_u32 s4, s11, s5
	s_add_u32 s11, s1, s10
	s_addc_u32 s12, s4, 0
	s_add_u32 s46, s11, 0x800
	s_addc_u32 s47, s12, 0
	s_add_u32 s48, s11, 0x1000
	s_addc_u32 s49, s12, 0
	s_ashr_i32 s1, s0, 31
	s_lshl_b64 s[4:5], s[0:1], 25
	s_add_u32 s20, s75, s4
	s_addc_u32 s21, s76, s5
	s_lshl_b64 s[4:5], s[2:3], 11
	s_add_u32 s4, s20, s4
	s_addc_u32 s5, s21, s5
	s_add_u32 s50, s4, s10
	s_addc_u32 s51, s5, 0
	s_lshl_b64 s[0:1], s[0:1], 19
	s_add_u32 s4, s77, s0
	s_addc_u32 s5, s78, s1
	s_lshl_b64 s[0:1], s[2:3], 5
	s_add_u32 s0, s4, s0
	s_addc_u32 s1, s5, s1
	s_lshl_b32 s2, s7, 2
	s_add_u32 s52, s0, s2
	s_addc_u32 s53, s1, 0
	s_lshl_b32 s82, s14, 8
	v_readfirstlane_b32 s0, v15
	s_lshl_b32 s79, 0x2400, s6
	s_lshl_b32 s80, 0x400, s6
	s_lshl_b32 s81, 8, s6
	s_lshr_b32 s83, 0x1000, s6
	s_ashr_i32 s4, s0, 1
	s_add_i32 s0, s82, 0xffffff80
	s_cmp_lg_u32 s14, 0
	s_cselect_b32 s0, s0, 0
	s_mul_hi_u32 s1, s0, s79
	s_mul_i32 s0, s0, s79
	s_lshl_b64 s[0:1], s[0:1], 1
	s_add_u32 s2, s11, s0
	v_ashrrev_i32_e32 v218, 4, v15
	s_addc_u32 s3, s12, s1
	s_add_u32 s0, s48, s0
	s_waitcnt vmcnt(0)
	v_mul_lo_u32 v2, s79, v218
	s_addc_u32 s1, s49, s1
	v_or_b32_e32 v2, v2, v0
	s_lshl_b32 s5, 0x48000, s6
	v_mov_b32_e32 v3, v1
	v_add_u32_e32 v4, s5, v2
	v_lshlrev_b64 v[18:19], 1, v[2:3]
	v_mov_b32_e32 v5, v1
	v_lshlrev_b64 v[20:21], 1, v[4:5]
	v_lshl_add_u64 v[2:3], s[2:3], 0, v[18:19]
	v_lshl_add_u64 v[4:5], s[2:3], 0, v[20:21]
	global_load_dwordx4 v[196:199], v[2:3], off offset:2048
	global_load_dwordx4 v[200:203], v[4:5], off offset:2048
	v_mov_b32_e32 v2, s4
	s_movk_i32 s2, 0xffe0
	v_bfi_b32 v2, s2, v2, v14
	v_mul_lo_u32 v2, v2, s79
	v_lshrrev_b32_e32 v3, 2, v14
	v_and_or_b32 v2, v3, 8, v2
	v_mov_b32_e32 v3, v1
	v_lshl_add_u64 v[2:3], v[2:3], 1, s[8:9]
	global_load_dwordx4 v[176:179], v[2:3], off
	global_load_dwordx4 v[172:175], v[2:3], off offset:32
	global_load_dwordx4 v[168:171], v[2:3], off offset:64
	global_load_dwordx4 v[164:167], v[2:3], off offset:96
	global_load_dwordx4 v[160:163], v[2:3], off offset:128
	global_load_dwordx4 v[10:13], v[2:3], off offset:160
	global_load_dwordx4 v[6:9], v[2:3], off offset:192
	s_nop 0
	global_load_dwordx4 v[2:5], v[2:3], off offset:224
	v_lshl_add_u64 v[18:19], s[0:1], 0, v[18:19]
	v_lshl_add_u64 v[20:21], s[0:1], 0, v[20:21]
	global_load_dwordx4 v[204:207], v[18:19], off
	global_load_dwordx4 v[208:211], v[20:21], off
	s_movk_i32 s0, 0x70
	v_lshlrev_b32_e32 v21, 1, v0
	v_lshlrev_b32_e32 v20, 8, v218
	s_waitcnt vmcnt(0)
	v_and_b32_e32 v22, 0xfffff0, v218
	v_lshlrev_b32_e32 v23, 1, v218
	v_bitop3_b32 v25, v21, v15, s0 bitop3:0x78
	v_and_or_b32 v22, v23, 8, v22
	v_add3_u32 v23, 0, v20, v25
	v_add_u32_e32 v25, 32, v218
	v_and_b32_e32 v26, 0xfffff0, v25
	v_lshlrev_b32_e32 v25, 1, v25
	v_and_or_b32 v25, v25, 8, v26
	v_bfe_u32 v17, v17, 5, 2
	v_lshrrev_b32_e32 v24, 1, v218
	v_lshrrev_b32_e32 v22, 1, v22
	s_waitcnt vmcnt(0)
	v_lshrrev_b32_e32 v25, 1, v25
	v_and_b32_e32 v19, 0x70, v15
	v_or_b32_e32 v22, v22, v17
	v_or_b32_e32 v17, v25, v17
	v_and_b32_e32 v18, 63, v14
	v_lshlrev_b32_e32 v22, 9, v22
	v_lshlrev_b32_e32 v17, 9, v17
	v_bitop3_b32 v19, v21, v20, v19 bitop3:0xde
	v_and_b32_e32 v219, 31, v14
	v_bfe_u32 v220, v14, 5, 1
	v_lshlrev_b32_e32 v20, 3, v18
	s_cmp_lg_u32 0, -1
	s_cselect_b32 s0, 0, 0
	v_lshlrev_b32_e32 v221, 2, v220
	v_sub_u32_e32 v222, v219, v221
	v_lshlrev_b32_e32 v224, 8, v219
	ds_write_b128 v23, v[196:199] offset:32768
	ds_write_b128 v23, v[200:203] offset:40960
	v_and_b32_e32 v23, 3, v218
	v_and_or_b32 v23, v24, 4, v23
	v_lshlrev_b32_e32 v23, 6, v23
	v_and_b32_e32 v24, 48, v21
	v_lshlrev_b32_e32 v21, 4, v14
	v_or3_b32 v22, v22, v23, v24
	v_or3_b32 v17, v17, v23, v24
	v_and_b32_e32 v23, 0xc0, v21
	v_lshlrev_b32_e32 v14, 1, v14
	v_and_or_b32 v23, v20, 24, v23
	v_and_b32_e32 v14, 32, v14
	v_and_b32_e32 v20, 0x100, v20
	v_or3_b32 v14, v23, v14, v20
	v_add_u32_e32 v223, s0, v14
	v_lshlrev_b32_e32 v14, 4, v220
	v_and_b32_e32 v20, 0x70, v21
	v_or_b32_e32 v21, 32, v14
	v_xad_u32 v225, v14, v20, 0
	v_xad_u32 v226, v21, v20, 0
	v_or_b32_e32 v21, 64, v14
	v_or_b32_e32 v14, 0x60, v14
	v_xad_u32 v227, v21, v20, 0
	v_xad_u32 v228, v14, v20, 0
	v_cmp_gt_u32_e64 s[6:7], 32, v18
	v_lshlrev_b32_e32 v14, 3, v220
	v_add_u32_e32 v229, 0xffffff80, v222
	v_add_u32_e32 v230, 0, v22
	v_add_u32_e32 v231, 0, v17
	v_add_u32_e32 v232, 0, v19
	s_mov_b32 s3, s79
	s_waitcnt lgkmcnt(0)
	s_barrier
	s_branch .LBB0_970

.LBB0_970:
	s_add_i32 s20, s72, s13
	s_cmpk_lt_i32 s20, 0x600
	s_cselect_b64 s[56:57], -1, 0
	s_cmpk_gt_i32 s20, 0x5ff
	s_cselect_b64 s[54:55], -1, 0
	s_and_b64 vcc, exec, s[54:55]
	s_mov_b64 s[58:59], s[8:9]
	s_mov_b64 s[60:61], s[46:47]
	s_mov_b64 s[62:63], s[48:49]
	s_mov_b64 s[64:65], s[50:51]
	s_mov_b64 s[66:67], s[52:53]
	s_mov_b32 s0, s79
	s_mov_b32 s14, s3
	s_mov_b32 s1, s80
	s_mov_b32 s10, s81
	s_mov_b32 s11, s82
	s_mov_b32 s12, s83
	s_cbranch_vccnz .LBB0_972
	s_sub_i32 s91, 0x5ff, s20
	s_ashr_i32 s0, s91, 9
	s_lshl_b32 s2, s0, 1
	s_lshr_b32 s5, 16, s2
	s_and_b32 s1, s91, 15
	s_sub_i32 s4, 4, s2
	s_add_i32 s5, s5, -1
	s_lshr_b32 s4, s1, s4
	s_and_b32 s14, s5, s1
	s_lshl_b32 s1, s91, 5
	s_and_b32 s1, s1, 0x3000
	s_or_b32 s1, s4, s1
	s_add_i32 s4, s2, 8
	s_bfe_u32 s12, s91, 0x30004
	s_lshl_b64 s[4:5], s[14:15], s4
	s_add_u32 s4, s4, s1
	s_addc_u32 s5, s5, 0
	s_mul_i32 s10, s5, 0x4800
	s_mul_hi_u32 s11, s4, 0x4800
	s_add_i32 s11, s11, s10
	s_mul_i32 s10, s4, 0x4800
	s_add_u32 s21, s73, s10
	s_mul_i32 s10, s0, 0xc00
	s_addc_u32 s22, s74, s11
	s_ashr_i32 s11, s10, 31
	s_lshl_b64 s[10:11], s[10:11], 1
	s_add_u32 s21, s21, s10
	s_addc_u32 s22, s22, s11
	s_lshl_b32 s23, s12, 8
	s_add_u32 s58, s21, s23
	s_addc_u32 s59, s22, 0
	s_mulk_i32 s1, 0x4800
	s_add_u32 s1, s73, s1
	s_addc_u32 s21, s74, 0
	s_add_u32 s1, s1, s10
	s_addc_u32 s10, s21, s11
	s_add_u32 s1, s1, s23
	s_addc_u32 s10, s10, 0
	s_add_u32 s60, s1, 0x800
	s_addc_u32 s61, s10, 0
	s_add_u32 s62, s1, 0x1000
	s_addc_u32 s63, s10, 0
	s_ashr_i32 s1, s0, 31
	s_lshl_b64 s[10:11], s[0:1], 25
	s_add_u32 s21, s75, s10
	s_addc_u32 s22, s76, s11
	s_lshl_b64 s[10:11], s[4:5], 11
	s_add_u32 s10, s21, s10
	s_addc_u32 s11, s22, s11
	s_add_u32 s64, s10, s23
	s_addc_u32 s65, s11, 0
	s_lshl_b64 s[0:1], s[0:1], 19
	s_add_u32 s10, s77, s0
	s_addc_u32 s11, s78, s1
	s_lshl_b64 s[0:1], s[4:5], 5
	s_add_u32 s0, s10, s0
	s_addc_u32 s1, s11, s1
	s_lshl_b32 s4, s12, 2
	s_add_u32 s66, s0, s4
	s_addc_u32 s67, s1, 0
	s_lshl_b32 s0, 0x2400, s2
	s_lshl_b32 s1, 0x400, s2
	s_lshl_b32 s10, 8, s2
	s_lshl_b32 s11, s14, 8
	s_lshr_b32 s12, 0x1000, s2
	s_mov_b32 s14, s0
